# nt cache hint on once-read loads in the P4 latent-norm, MLA-prep and P7 GLA-norm loops
# baseline (speedup 1.0000x reference)
; __device__ __forceinline__ unsigned pk2(float lo, float hi) { f32x2_t v = {lo, hi}; bf16x2_t b = __builtin_convertvector(v, bf16x2_t); return __builtin_bit_cast(unsigned, b); }
; __global__ void __launch_bounds__(512, 2) mega_fwd(Args args) {
;     ...
;         for (int m = gw; m < T; m += NGW) {
;             const bf16_t* zr = Z + (size_t)m * ZLD;
;             {
;                 const int h_ = lane >> 4, pc = lane & 15, fr_ = m & 15, fw_ = (m >> 4) & 3, ch_ = (m >> 6) & 31, b_ = m >> 11;
;                 const u32x4 gqv = *(const u32x4*)(zr + ZGQ + h_ * 128 + pc * 8);
;                 *(u32x4*)(H + ((((size_t)((b_ * 4 + h_) * 32 + ch_) * 4 + fw_) * 4 + (pc >> 2)) * 64 + (pc & 3) * 16 + fr_) * 8) = gqv;
;             }
;             {
;                 const u32x4 u = *(const u32x4*)(zr + ZQ + lane * 8);
;                 float v[8] = {bflo(u.x), bfhi(u.x), bflo(u.y), bfhi(u.y), bflo(u.z), bfhi(u.z), bflo(u.w), bfhi(u.w)};
;                 float sq = 0.f;
; #pragma unroll
;                 for (int e = 0; e < 8; ++e) sq += v[e] * v[e];
;                 const float r = rsqrtf(wave_sum(sq) * (1.f / 512.f) + EPS);
;                 const f32x4 g0 = *(const f32x4*)(args.in[9] + lane * 8), g1 = *(const f32x4*)(args.in[9] + lane * 8 + 4);
;                 u32x4 w; w.x = pk2(v[0] * r * g0.x, v[1] * r * g0.y); w.y = pk2(v[2] * r * g0.z, v[3] * r * g0.w); w.z = pk2(v[4] * r * g1.x, v[5] * r * g1.y); w.w = pk2(v[6] * r * g1.z, v[7] * r * g1.w);
;                 *(u32x4*)(QA + (size_t)m * 512 + lane * 8) = w;
;             }
;             {
;                 const u32x2 u = *(const u32x2*)(zr + ZKV + lane * 4);
;                 const float v0 = bflo(u.x), v1 = bfhi(u.x), v2 = bflo(u.y), v3 = bfhi(u.y);
;                 const float r = rsqrtf(wave_sum(v0 * v0 + v1 * v1 + v2 * v2 + v3 * v3) * (1.f / 256.f) + EPS);
;                 const f32x4 g0 = *(const f32x4*)(args.in[11] + lane * 4);
;                 u32x2 w; w.x = pk2(v0 * r * g0.x, v1 * r * g0.y); w.y = pk2(v2 * r * g0.z, v3 * r * g0.w);
;                 *(u32x2*)(KVA + (size_t)m * 256 + lane * 4) = w;
;             }
;         }
.LBB0_600:
	v_readlane_b32 s0, v238, 38
	s_cmpk_gt_i32 s0, 0x3fff
	v_readlane_b32 s1, v238, 39
	s_cbranch_scc1 .LBB0_603
	v_readlane_b32 s60, v238, 5
	v_readlane_b32 s62, v238, 7
	v_readlane_b32 s63, v238, 8
	v_mov_b32_e32 v17, 0
	v_lshlrev_b32_e32 v16, 5, v184
	v_readlane_b32 s66, v238, 11
	v_readlane_b32 s67, v238, 12
	v_readlane_b32 s70, v238, 15
	v_readlane_b32 s71, v238, 16
	s_mov_b64 s[2:3], s[62:63]
	v_readlane_b32 s0, v238, 38
	s_mov_b64 s[6:7], s[66:67]
	s_mov_b64 s[10:11], s[70:71]
	v_lshl_add_u64 v[4:5], s[2:3], 0, v[16:17]
	v_lshlrev_b32_e32 v16, 4, v184
	s_mov_b32 s12, s0
	v_and_b32_e32 v3, 15, v185
	v_lshlrev_b32_e32 v12, 3, v184
	v_lshl_add_u64 v[6:7], s[6:7], 0, v[16:17]
	v_readlane_b32 s1, v238, 39
	s_ashr_i32 s13, s0, 31
	s_mul_hi_i32 s6, s12, 0x1800
	s_mul_i32 s10, s12, 0x1800
	s_lshl_b64 s[0:1], s[12:13], 9
	v_or_b32_e32 v18, s10, v12
	v_mov_b32_e32 v19, s6
	s_mov_b64 s[6:7], 0xa800400
	v_and_b32_e32 v14, 0x300, v16
	v_lshlrev_b32_e32 v3, 4, v3
	v_or_b32_e32 v8, s0, v12
	s_lshl_b64 s[2:3], s[12:13], 10
	v_lshl_add_u64 v[12:13], v[18:19], 0, s[6:7]
	v_or3_b32 v18, s10, v14, v3
	s_mov_b64 s[8:9], 0xa800680
	v_lshlrev_b32_e32 v2, 4, v185
	v_mov_b32_e32 v9, s1
	s_mov_b64 s[0:1], 0x13800000
	s_ashr_i32 s97, s96, 31
	v_or_b32_e32 v10, s2, v16
	v_mov_b32_e32 v11, s3
	s_mov_b64 s[2:3], 0x12800000
	v_lshl_add_u64 v[14:15], v[18:19], 0, s[8:9]
	v_or_b32_e32 v18, s10, v16
	s_mov_b64 s[8:9], 0xa800000
	s_mov_b32 s10, s12
	v_lshrrev_b32_e32 v1, 4, v184
	v_bfe_u32 v0, v185, 2, 2
	v_and_b32_e32 v2, 48, v2
	v_readlane_b32 s61, v238, 6
	v_readlane_b32 s64, v238, 9
	v_readlane_b32 s65, v238, 10
	v_readlane_b32 s68, v238, 13
	v_readlane_b32 s69, v238, 14
	v_readlane_b32 s72, v238, 17
	v_readlane_b32 s73, v238, 18
	v_readlane_b32 s74, v238, 19
	v_readlane_b32 s75, v238, 20
	v_lshl_add_u64 v[8:9], v[8:9], 0, s[0:1]
	s_lshl_b64 s[0:1], s[96:97], 9
	v_lshl_add_u64 v[10:11], v[10:11], 0, s[2:3]
	s_lshl_b64 s[2:3], s[96:97], 10
	s_mul_hi_i32 s7, s96, 0x1800
	s_mul_i32 s6, s96, 0x1800
	v_lshl_add_u64 v[16:17], v[18:19], 0, s[8:9]
	v_mov_b32_e32 v3, 0x358637bd
	s_mov_b32 s8, 0x800000
	v_writelane_b32 v238, s10, 38
	s_mov_b32 s9, s12
	s_nop 0
	v_writelane_b32 v238, s11, 39
	global_load_dwordx4 v[60:63], v[4:5], off nt
	global_load_dwordx4 v[64:67], v[4:5], off offset:16 nt
	global_load_dwordx4 v[68:71], v[6:7], off nt
; __device__ __forceinline__ unsigned pk2(float lo, float hi) { f32x2_t v = {lo, hi}; bf16x2_t b = __builtin_convertvector(v, bf16x2_t); return __builtin_bit_cast(unsigned, b); }
; __global__ void __launch_bounds__(512, 2) mega_fwd(Args args) {
;     ...
;         for (int m = gw; m < T; m += NGW) {
;             const bf16_t* zr = Z + (size_t)m * ZLD;
;             {
;                 const int h_ = lane >> 4, pc = lane & 15, fr_ = m & 15, fw_ = (m >> 4) & 3, ch_ = (m >> 6) & 31, b_ = m >> 11;
;                 const u32x4 gqv = *(const u32x4*)(zr + ZGQ + h_ * 128 + pc * 8);
;                 *(u32x4*)(H + ((((size_t)((b_ * 4 + h_) * 32 + ch_) * 4 + fw_) * 4 + (pc >> 2)) * 64 + (pc & 3) * 16 + fr_) * 8) = gqv;
;             }
;             {
;                 const u32x4 u = *(const u32x4*)(zr + ZQ + lane * 8);
;                 float v[8] = {bflo(u.x), bfhi(u.x), bflo(u.y), bfhi(u.y), bflo(u.z), bfhi(u.z), bflo(u.w), bfhi(u.w)};
;                 float sq = 0.f;
; #pragma unroll
;                 for (int e = 0; e < 8; ++e) sq += v[e] * v[e];
;                 const float r = rsqrtf(wave_sum(sq) * (1.f / 512.f) + EPS);
;                 const f32x4 g0 = *(const f32x4*)(args.in[9] + lane * 8), g1 = *(const f32x4*)(args.in[9] + lane * 8 + 4);
;                 u32x4 w; w.x = pk2(v[0] * r * g0.x, v[1] * r * g0.y); w.y = pk2(v[2] * r * g0.z, v[3] * r * g0.w); w.z = pk2(v[4] * r * g1.x, v[5] * r * g1.y); w.w = pk2(v[6] * r * g1.z, v[7] * r * g1.w);
;                 *(u32x4*)(QA + (size_t)m * 512 + lane * 8) = w;
;             }
;             {
;                 const u32x2 u = *(const u32x2*)(zr + ZKV + lane * 4);
;                 const float v0 = bflo(u.x), v1 = bfhi(u.x), v2 = bflo(u.y), v3 = bfhi(u.y);
;                 const float r = rsqrtf(wave_sum(v0 * v0 + v1 * v1 + v2 * v2 + v3 * v3) * (1.f / 256.f) + EPS);
;                 const f32x4 g0 = *(const f32x4*)(args.in[11] + lane * 4);
;                 u32x2 w; w.x = pk2(v0 * r * g0.x, v1 * r * g0.y); w.y = pk2(v2 * r * g0.z, v3 * r * g0.w);
;                 *(u32x2*)(KVA + (size_t)m * 256 + lane * 4) = w;
;             }
;         }
.LBB0_602:
	v_lshl_add_u64 v[18:19], s[86:87], 0, v[14:15]
	v_lshl_add_u64 v[22:23], s[86:87], 0, v[16:17]
	v_lshl_add_u64 v[32:33], s[86:87], 0, v[12:13]
	global_load_dwordx4 v[52:55], v[18:19], off nt
	global_load_dwordx4 v[46:49], v[22:23], off nt
	global_load_dwordx2 v[50:51], v[32:33], off nt
	s_ashr_i32 s11, s9, 9
	s_and_b32 s11, s11, 0x7fffffc
	s_bfe_u32 s10, s9, 0x50006
	v_or_b32_e32 v24, s11, v1
	v_lshl_or_b32 v24, v24, 5, s10
	v_ashrrev_i32_e32 v25, 31, v24
	s_lshr_b32 s12, s9, 2
	v_lshlrev_b64 v[24:25], 4, v[24:25]
	v_and_or_b32 v24, s12, 12, v24
	v_or_b32_e32 v24, v24, v0
	v_lshlrev_b64 v[24:25], 6, v[24:25]
	v_or_b32_e32 v24, v24, v2
	v_and_or_b32 v24, s9, 15, v24
	v_lshl_add_u64 v[24:25], v[24:25], 4, s[40:41]
	v_lshl_add_u64 v[30:31], s[86:87], 0, v[10:11]
	s_add_i32 s9, s9, s96
	v_lshl_add_u64 v[10:11], v[10:11], 0, s[2:3]
	v_lshl_add_u64 v[12:13], v[12:13], 0, s[6:7]
	v_lshl_add_u64 v[14:15], v[14:15], 0, s[6:7]
	v_lshl_add_u64 v[16:17], v[16:17], 0, s[6:7]
	s_cmpk_gt_i32 s9, 0x3fff
	s_waitcnt vmcnt(2)
	global_store_dwordx4 v[24:25], v[52:55], off
	s_waitcnt vmcnt(2)
	v_lshlrev_b32_e32 v38, 16, v46
	v_and_b32_e32 v39, 0xffff0000, v46
	v_lshlrev_b32_e32 v34, 16, v49
	v_and_b32_e32 v35, 0xffff0000, v49
	v_lshlrev_b32_e32 v36, 16, v48
	v_and_b32_e32 v37, 0xffff0000, v48
	v_lshlrev_b32_e32 v20, 16, v47
	v_and_b32_e32 v21, 0xffff0000, v47
	v_pk_mul_f32 v[44:45], v[38:39], v[38:39]
	v_pk_mul_f32 v[42:43], v[20:21], v[20:21]
	v_add_f32_e32 v44, v44, v45
	v_add_f32_e32 v42, v44, v42
	v_pk_mul_f32 v[40:41], v[36:37], v[36:37]
	v_add_f32_e32 v42, v42, v43
	v_add_f32_e32 v40, v42, v40
	v_pk_mul_f32 v[18:19], v[34:35], v[34:35]
	v_add_f32_e32 v40, v40, v41
	v_add_f32_e32 v18, v40, v18
	v_add_f32_e32 v18, v18, v19
	s_nop 1
	v_add_f32_dpp v18, v18, v18 quad_perm:[1,0,3,2] row_mask:0xf bank_mask:0xf bound_ctrl:1
	s_nop 1
	v_add_f32_dpp v18, v18, v18 quad_perm:[2,3,0,1] row_mask:0xf bank_mask:0xf bound_ctrl:1
	s_nop 1
	v_add_f32_dpp v18, v18, v18 row_half_mirror row_mask:0xf bank_mask:0xf bound_ctrl:1
	s_nop 1
	v_add_f32_dpp v18, v18, v18 row_mirror row_mask:0xf bank_mask:0xf bound_ctrl:1
	s_nop 0
	v_readlane_b32 s12, v18, 16
	v_readlane_b32 s13, v18, 48
	v_readlane_b32 s10, v18, 0
	v_readlane_b32 s11, v18, 32
	v_mov_b32_e32 v18, s12
	v_mov_b32_e32 v19, s13
	v_pk_add_f32 v[18:19], s[10:11], v[18:19]
	s_nop 0
	v_add_f32_e32 v18, v18, v19
	v_fmamk_f32 v18, v18, 0x3b000000, v3
	v_mul_f32_e32 v19, 0x4b800000, v18
	v_cmp_gt_f32_e32 vcc, s8, v18
	s_nop 1
	v_cndmask_b32_e32 v18, v18, v19, vcc
	v_rsq_f32_e32 v18, v18
	s_nop 0
	v_mul_f32_e32 v19, 0x45800000, v18
	v_cndmask_b32_e32 v18, v18, v19, vcc
	v_pk_mul_f32 v[38:39], v[18:19], v[38:39] op_sel_hi:[0,1]
	v_pk_mul_f32 v[20:21], v[18:19], v[20:21] op_sel_hi:[0,1]
	v_pk_mul_f32 v[36:37], v[18:19], v[36:37] op_sel_hi:[0,1]
	v_pk_mul_f32 v[18:19], v[18:19], v[34:35] op_sel_hi:[0,1]
	v_pk_mul_f32 v[22:23], v[60:61], v[38:39]
	v_pk_mul_f32 v[20:21], v[62:63], v[20:21]
	v_pk_mul_f32 v[24:25], v[64:65], v[36:37]
	v_pk_mul_f32 v[26:27], v[66:67], v[18:19]
	v_cvt_pk_bf16_f32 v18, v22, v23
	v_cvt_pk_bf16_f32 v19, v20, v21
	v_cvt_pk_bf16_f32 v20, v24, v25
	v_cvt_pk_bf16_f32 v21, v26, v27
	global_store_dwordx4 v[30:31], v[18:21], off
	v_lshl_add_u64 v[24:25], s[86:87], 0, v[8:9]
	v_lshl_add_u64 v[8:9], v[8:9], 0, s[0:1]
	s_waitcnt vmcnt(2)
	v_lshlrev_b32_e32 v28, 16, v50
	v_and_b32_e32 v29, 0xffff0000, v50
	v_lshlrev_b32_e32 v26, 16, v51
	v_and_b32_e32 v27, 0xffff0000, v51
	v_pk_mul_f32 v[30:31], v[28:29], v[28:29]
	v_pk_mul_f32 v[22:23], v[26:27], v[26:27]
	v_add_f32_e32 v30, v30, v31
	v_add_f32_e32 v22, v22, v30
	v_add_f32_e32 v22, v23, v22
	s_nop 1
	v_add_f32_dpp v22, v22, v22 quad_perm:[1,0,3,2] row_mask:0xf bank_mask:0xf bound_ctrl:1
	s_nop 1
	v_add_f32_dpp v22, v22, v22 quad_perm:[2,3,0,1] row_mask:0xf bank_mask:0xf bound_ctrl:1
	s_nop 1
	v_add_f32_dpp v22, v22, v22 row_half_mirror row_mask:0xf bank_mask:0xf bound_ctrl:1
	s_nop 1
	v_add_f32_dpp v22, v22, v22 row_mirror row_mask:0xf bank_mask:0xf bound_ctrl:1
	s_nop 0
	v_readlane_b32 s12, v22, 16
	v_readlane_b32 s13, v22, 48
	v_readlane_b32 s10, v22, 0
	v_readlane_b32 s11, v22, 32
	v_mov_b32_e32 v22, s12
	v_mov_b32_e32 v23, s13
	v_pk_add_f32 v[22:23], s[10:11], v[22:23]
	s_nop 0
	v_add_f32_e32 v22, v22, v23
	v_fmamk_f32 v22, v22, 0x3b800000, v3
	v_mul_f32_e32 v23, 0x4b800000, v22
	v_cmp_gt_f32_e32 vcc, s8, v22
	s_nop 1
	v_cndmask_b32_e32 v22, v22, v23, vcc
	v_rsq_f32_e32 v22, v22
	s_nop 0
	v_mul_f32_e32 v23, 0x45800000, v22
	v_cndmask_b32_e32 v22, v22, v23, vcc
	v_pk_mul_f32 v[28:29], v[22:23], v[28:29] op_sel_hi:[0,1]
	v_pk_mul_f32 v[22:23], v[22:23], v[26:27] op_sel_hi:[0,1]
	v_pk_mul_f32 v[18:19], v[68:69], v[28:29]
	v_pk_mul_f32 v[20:21], v[70:71], v[22:23]
	v_cvt_pk_bf16_f32 v18, v18, v19
	v_cvt_pk_bf16_f32 v19, v20, v21
	global_store_dwordx2 v[24:25], v[18:19], off
	s_cbranch_scc0 .LBB0_602

; __global__ void __launch_bounds__(512, 2) mega_fwd(Args args) {
;     ...
;             const int hh = lane >> 3, jj = lane & 7;
;             const float* gqn = args.in[13]; const float* gkn = args.in[14];
;             f32x4 gq[4], gk[4];
; #pragma unroll
;             for (int i = 0; i < 4; ++i) { gq[i] = *(const f32x4*)(gqn + 16 * jj + 4 * i); gk[i] = *(const f32x4*)(gkn + 16 * jj + 4 * i); }
;             const f32x4 gq1 = *(const f32x4*)(gqn + 128 + 4 * jj), gq2 = *(const f32x4*)(gqn + 160 + 4 * jj), gk1 = *(const f32x4*)(gkn + 128 + 4 * jj), gk2 = *(const f32x4*)(gkn + 160 + 4 * jj);
;             float ifr[4];
; #pragma unroll
;             for (int e = 0; e < 4; ++e) ifr[e] = exp2f(-(float)(4 * jj + e) * (13.287712379549449f / 32.f));
;             const float qsc = 0.07216878364870322f * LOG2E;
;             u32x4 nqa0, nqa1, nka0, nka1; u32x2 nqr1, nqr2, nkr1, nkr2; int npos;
;     ...
;             if (gw < T) MLAP_LOAD(gw);
.LBB0_988:
	global_load_dwordx4 v[0:3], v[82:83], off offset:48 nt
	global_load_dwordx4 v[4:7], v[82:83], off offset:32 nt
	global_load_dwordx4 v[8:11], v[82:83], off offset:16 nt
	global_load_dwordx4 v[12:15], v[82:83], off nt
	global_load_dwordx4 v[16:19], v[84:85], off offset:48 nt
	global_load_dwordx4 v[20:23], v[84:85], off offset:32 nt
	global_load_dwordx4 v[24:27], v[84:85], off offset:16 nt
	global_load_dwordx4 v[28:31], v[84:85], off nt
	global_load_dwordx4 v[32:35], v[86:87], off offset:512 nt
	global_load_dwordx4 v[36:39], v[86:87], off offset:640 nt
	global_load_dwordx4 v[40:43], v[88:89], off offset:512 nt
	global_load_dwordx4 v[44:47], v[88:89], off offset:640 nt
	s_waitcnt vmcnt(23)
	v_mov_b64_e32 v[70:71], v[62:63]
	v_mov_b64_e32 v[66:67], v[58:59]
	v_mov_b64_e32 v[78:79], v[54:55]
	v_mov_b64_e32 v[74:75], v[50:51]
	v_cmp_ne_u32_e64 s[0:1], 1, v146
	s_andn2_b64 vcc, exec, s[2:3]
	s_waitcnt vmcnt(20)
	v_mov_b32_e32 v126, v147
	v_mov_b64_e32 v[128:129], v[118:119]
	v_mov_b64_e32 v[132:133], v[112:113]
	v_mov_b64_e32 v[138:139], v[110:111]
	v_mov_b64_e32 v[140:141], v[108:109]
	v_mov_b64_e32 v[68:69], v[60:61]
	v_mov_b64_e32 v[64:65], v[56:57]
	v_mov_b64_e32 v[76:77], v[52:53]
	v_mov_b64_e32 v[72:73], v[48:49]
	s_cbranch_vccnz .LBB0_990
	global_load_dwordx4 v[76:79], v[90:91], off offset:16 nt
	global_load_dwordx4 v[72:75], v[90:91], off nt
	v_lshl_add_u64 v[220:221], v[92:93], 0, v[240:241]
	global_load_dwordx4 v[212:215], v[220:221], off offset:256 nt
	s_nop 0
	global_load_dwordx4 v[68:71], v[94:95], off offset:16 nt
	global_load_dwordx4 v[64:67], v[94:95], off nt
	v_lshl_add_u64 v[222:223], v[96:97], 0, v[240:241]
	global_load_dwordx4 v[216:219], v[222:223], off offset:1536 nt
	s_nop 0
	global_load_dword v126, v81, s[22:23] nt

; __global__ void __launch_bounds__(512, 2) mega_fwd(Args args) {
;     ...
;             if (gw < T) MLAP_LOAD(gw);
;             for (int m = gw; m < T; m += NGW) {
;                 bf16_t* qp = Qb + (size_t)m * 1536 + hh * 192; bf16_t* kp = Kb + (size_t)m * 1536 + hh * 192;
;                 const u32x4 qa0 = nqa0, qa1 = nqa1, ka0 = nka0, ka1 = nka1; const u32x2 qr1 = nqr1, qr2 = nqr2, kr1 = nkr1, kr2 = nkr2;
;                 const float pos = (float)npos;
;                 if (m + NGW < T) MLAP_LOAD(m + NGW);
.LBB0_992:
	s_add_i32 s34, s34, s96
	s_cmpk_gt_i32 s34, 0x3fff
	s_cselect_b64 s[52:53], -1, 0
	s_and_b64 vcc, exec, s[52:53]
	s_cbranch_vccnz .LBB0_994
	v_lshl_add_u64 v[56:57], s[86:87], 0, v[122:123]
	v_add_co_u32_e32 v48, vcc, 0x15800000, v56
	v_lshl_add_u64 v[58:59], s[86:87], 0, v[120:121]
	s_nop 0
	v_addc_co_u32_e32 v49, vcc, 0, v57, vcc
	v_add_co_u32_e32 v58, vcc, 0x15800000, v58
	v_lshl_add_u64 v[52:53], v[56:57], 0, s[42:43]
	s_nop 0
	v_addc_co_u32_e32 v59, vcc, 0, v59, vcc
	v_lshl_add_u64 v[60:61], v[56:57], 0, s[44:45]
	v_add_co_u32_e32 v56, vcc, 0x18800000, v56
	v_lshl_add_u64 v[112:113], s[86:87], 0, v[124:125]
	s_nop 0
	v_addc_co_u32_e32 v57, vcc, 0, v57, vcc
	v_add_co_u32_e32 v118, vcc, 0xa800000, v112
	global_load_dwordx4 v[48:51], v[48:49], off nt
	s_nop 0
	global_load_dwordx4 v[52:55], v[52:53], off offset:16 nt
	v_addc_co_u32_e32 v119, vcc, 0, v113, vcc
	v_lshl_add_u64 v[220:221], v[58:59], 0, v[240:241]
	global_load_dwordx4 v[212:215], v[220:221], off offset:256 nt
	s_nop 0
	global_load_dwordx4 v[56:59], v[56:57], off nt
	s_nop 0
	global_load_dwordx4 v[60:63], v[60:61], off offset:16 nt
	s_nop 0
	v_lshl_add_u64 v[222:223], v[118:119], 0, v[240:241]
	global_load_dwordx4 v[216:219], v[222:223], off offset:1536 nt
	s_nop 0
	s_nop 0
	s_nop 0
	global_load_dword v147, v81, s[50:51] nt

; __device__ __forceinline__ unsigned pk2(float lo, float hi) { f32x2_t v = {lo, hi}; bf16x2_t b = __builtin_convertvector(v, bf16x2_t); return __builtin_bit_cast(unsigned, b); }
; __device__ __forceinline__ float fast_silu(float g) { return g * __builtin_amdgcn_rcpf(1.f + __expf(-g)); }
; __global__ void __launch_bounds__(512, 2) mega_fwd(Args args) {
;     ...
;     if (IN(7)) {
;         {
;             const f32x4 gg = *(const f32x4*)(args.in[17] + lane * 4);
;             for (int m = gw; m < T; m += NGW) {
;                 u32x2 u[4], zu[4];
; #pragma unroll
;                 for (int h = 0; h < 4; ++h) {
;                     u[h] = *(const u32x2*)(OG + (size_t)(((m >> 11) * 4 + h) * 8 + (lane >> 3)) * (SEQ * 32) + (size_t)(m & 2047) * 32 + (lane & 7) * 4);
;                     zu[h] = *(const u32x2*)(Z + (size_t)m * ZLD + ZZR + h * 256 + lane * 4); }
; #pragma unroll
;                 for (int h = 0; h < 4; ++h) {
;                     const float v0 = bflo(u[h].x), v1 = bfhi(u[h].x), v2 = bflo(u[h].y), v3 = bfhi(u[h].y);
;                     const float r = rsqrtf(wave_sum(v0 * v0 + v1 * v1 + v2 * v2 + v3 * v3) * (1.f / 256.f) + EPS);
;                     const float z0 = bflo(zu[h].x), z1 = bfhi(zu[h].x), z2 = bflo(zu[h].y), z3 = bfhi(zu[h].y);
;                     u32x2 w; w.x = pk2(v0 * r * gg.x * fast_silu(z0), v1 * r * gg.y * fast_silu(z1));
;                     w.y = pk2(v2 * r * gg.z * fast_silu(z2), v3 * r * gg.w * fast_silu(z3));
;                     *(u32x2*)(CAT + (size_t)m * 2048 + 1024 + h * 256 + lane * 4) = w;
;                 }
.LBB0_1050:
	s_cmp_lt_i32 s92, 8
	s_cselect_b64 s[2:3], -1, 0
	s_and_b64 s[60:61], s[2:3], s[0:1]
	s_andn2_b64 vcc, exec, s[60:61]
	s_cbranch_vccnz .LBB0_1131
	s_cmpk_gt_i32 s82, 0x3fff
	s_cbranch_scc1 .LBB0_1054
	v_readlane_b32 s44, v238, 21
	v_lshlrev_b32_e32 v0, 4, v184
	v_readlane_b32 s46, v238, 23
	v_readlane_b32 s47, v238, 24
	s_ashr_i32 s83, s82, 31
	s_lshl_b64 s[0:1], s[82:83], 12
	s_add_u32 s12, s86, s0
	s_addc_u32 s13, s87, s1
	s_ashr_i32 s97, s96, 31
	global_load_dwordx4 v[0:3], v0, s[46:47]
	s_lshl_b64 s[24:25], s[96:97], 12
	s_mul_i32 s1, s82, 0x1800
	s_mul_hi_i32 s0, s82, 0x1800
	s_add_u32 s26, s86, s1
	s_waitcnt vmcnt(0)
	v_lshlrev_b32_e32 v4, 3, v185
	s_addc_u32 s27, s87, s0
	s_lshl_b32 s0, s80, 8
	s_lshl_b32 s1, s90, 5
	v_lshrrev_b32_e32 v14, 3, v184
	v_and_b32_e32 v4, 56, v4
	v_mov_b32_e32 v5, 0
	s_add_i32 s17, s0, s1
	s_mov_b32 s0, 0x358637bd
	v_lshl_add_u64 v[6:7], s[4:5], 0, v[4:5]
	v_or_b32_e32 v15, 8, v14
	v_or_b32_e32 v16, 16, v14
	v_or_b32_e32 v17, 24, v14
	v_lshlrev_b32_e32 v4, 3, v184
	v_and_b32_e32 v252, 1, v184
	v_mov_b32_e32 v253, 0
	v_mov_b32_e32 v255, 0
	v_mul_u32_u24_e32 v254, 0xffff8, v252
	v_mul_u32_u24_e32 v252, 0x1f8, v252
	s_mul_hi_i32 s14, s96, 0x1800
	s_mul_i32 s16, s96, 0x1800
	s_lshl_b32 s22, s15, 8
	s_mov_b32 s29, 0
	s_mov_b32 s23, 0xa800000
	s_mov_b32 s33, 0xa801000
	s_mov_b32 s36, 0x3b800000
	v_mov_b64_e32 v[8:9], s[0:1]
	s_mov_b32 s34, 0x800000
	s_mov_b32 s35, 0x6800000
	s_mov_b32 s37, s82
	v_readlane_b32 s45, v238, 22
	v_readlane_b32 s48, v238, 25
	v_readlane_b32 s49, v238, 26
	v_readlane_b32 s50, v238, 27
	v_readlane_b32 s51, v238, 28
	v_readlane_b32 s52, v238, 29
	v_readlane_b32 s53, v238, 30
	v_readlane_b32 s54, v238, 31
	v_readlane_b32 s55, v238, 32
	v_readlane_b32 s56, v238, 33
	v_readlane_b32 s57, v238, 34
	v_readlane_b32 s58, v238, 35
	v_readlane_b32 s59, v238, 36
	v_lshl_add_u64 v[110:111], s[26:27], 0, v[4:5]
	v_add_co_u32_e32 v118, vcc, s23, v110
	s_ashr_i32 s0, s37, 9
	s_nop 0
	v_addc_co_u32_e32 v119, vcc, 0, v111, vcc
	v_add_co_u32_e32 v120, vcc, s33, v110
	v_lshl_add_u64 v[112:113], s[12:13], 0, v[4:5]
	s_nop 0
	v_addc_co_u32_e32 v121, vcc, 0, v111, vcc
	s_and_b32 s1, s17, 0xffe0
	s_lshl_b32 s0, s0, 3
	v_add_co_u32_e32 v110, vcc, s35, v112
	s_lshl_b32 s28, s1, 1
	s_nop 0
	v_addc_co_u32_e32 v111, vcc, 0, v113, vcc
	v_lshl_add_u64 v[118:119], v[118:119], 0, v[252:253]
	v_lshl_add_u64 v[120:121], v[120:121], 0, v[252:253]
	global_load_dwordx4 v[88:91], v[118:119], off offset:3744 nt
	s_nop 0
	s_nop 0
	global_load_dwordx4 v[92:95], v[120:121], off offset:672 nt
	s_nop 0
	s_nop 0
	s_and_b32 s1, s0, 0xffffffe0
	v_or_b32_e32 v126, s0, v17
	v_or_b32_e32 v128, s1, v14
	v_or_b32_e32 v130, s1, v15
	v_or_b32_e32 v132, s1, v16
	v_ashrrev_i32_e32 v127, 31, v126
	v_ashrrev_i32_e32 v129, 31, v128
	v_ashrrev_i32_e32 v131, 31, v130
	v_ashrrev_i32_e32 v133, 31, v132
	v_lshl_add_u64 v[124:125], v[6:7], 0, s[28:29]
	v_lshlrev_b64 v[126:127], 17, v[126:127]
	v_lshlrev_b64 v[128:129], 17, v[128:129]
	v_lshlrev_b64 v[130:131], 17, v[130:131]
	v_lshlrev_b64 v[132:133], 17, v[132:133]
	v_lshl_add_u64 v[126:127], v[124:125], 0, v[126:127]
	v_lshl_add_u64 v[128:129], v[124:125], 0, v[128:129]
	v_lshl_add_u64 v[130:131], v[124:125], 0, v[130:131]
	v_lshl_add_u64 v[124:125], v[124:125], 0, v[132:133]
	v_lshl_add_u64 v[128:129], v[128:129], 0, v[254:255]
	v_lshl_add_u64 v[124:125], v[124:125], 0, v[254:255]
	global_load_dwordx4 v[96:99], v[128:129], off nt
	s_nop 0
	s_nop 0
	s_nop 0
	global_load_dwordx4 v[100:103], v[124:125], off nt
	s_nop 0
	s_nop 0
	s_add_i32 s37, s37, s96
	s_add_u32 s12, s12, s24
	s_addc_u32 s13, s13, s25
	s_add_u32 s26, s26, s16
	s_addc_u32 s27, s27, s14
	s_add_i32 s17, s17, s22
	s_cmpk_gt_i32 s37, 0x3fff
	s_cselect_b32 s50, 1, 0
	s_waitcnt vmcnt(0)
	v_and_b32_e32 v246, 1, v184
	v_lshrrev_b32_e32 v247, 1, v184
	v_lshlrev_b32_e32 v246, 9, v246
	v_lshl_add_u32 v246, v247, 4, v246
	v_lshlrev_b32_e32 v247, 3, v184
	v_sub_u32_e32 v246, v246, v247
	v_ashrrev_i32_e32 v247, 31, v246
	s_mov_b32 s62, 0xaaaaaaaa
	s_mov_b32 s63, 0xaaaaaaaa
; __device__ __forceinline__ unsigned pk2(float lo, float hi) { f32x2_t v = {lo, hi}; bf16x2_t b = __builtin_convertvector(v, bf16x2_t); return __builtin_bit_cast(unsigned, b); }
; __device__ __forceinline__ float fast_silu(float g) { return g * __builtin_amdgcn_rcpf(1.f + __expf(-g)); }
; __global__ void __launch_bounds__(512, 2) mega_fwd(Args args) {
;     ...
;             for (int m = gw; m < T; m += NGW) {
;                 u32x2 u[4], zu[4];
; #pragma unroll
;                 for (int h = 0; h < 4; ++h) {
;                     u[h] = *(const u32x2*)(OG + (size_t)(((m >> 11) * 4 + h) * 8 + (lane >> 3)) * (SEQ * 32) + (size_t)(m & 2047) * 32 + (lane & 7) * 4);
;                     zu[h] = *(const u32x2*)(Z + (size_t)m * ZLD + ZZR + h * 256 + lane * 4); }
; #pragma unroll
;                 for (int h = 0; h < 4; ++h) {
;                     const float v0 = bflo(u[h].x), v1 = bfhi(u[h].x), v2 = bflo(u[h].y), v3 = bfhi(u[h].y);
;                     const float r = rsqrtf(wave_sum(v0 * v0 + v1 * v1 + v2 * v2 + v3 * v3) * (1.f / 256.f) + EPS);
;                     const float z0 = bflo(zu[h].x), z1 = bfhi(zu[h].x), z2 = bflo(zu[h].y), z3 = bfhi(zu[h].y);
;                     u32x2 w; w.x = pk2(v0 * r * gg.x * fast_silu(z0), v1 * r * gg.y * fast_silu(z1));
;                     w.y = pk2(v2 * r * gg.z * fast_silu(z2), v3 * r * gg.w * fast_silu(z3));
;                     *(u32x2*)(CAT + (size_t)m * 2048 + 1024 + h * 256 + lane * 4) = w;
;                 }
.LBB0_1053:
	v_mov_b32_dpp v248, v88 quad_perm:[1,0,3,2] row_mask:0xf bank_mask:0xf
	v_mov_b32_dpp v249, v89 quad_perm:[1,0,3,2] row_mask:0xf bank_mask:0xf
	v_mov_b32_dpp v250, v90 quad_perm:[1,0,3,2] row_mask:0xf bank_mask:0xf
	v_mov_b32_dpp v251, v91 quad_perm:[1,0,3,2] row_mask:0xf bank_mask:0xf
	v_cndmask_b32_e64 v12, v88, v250, s[62:63]
	v_cndmask_b32_e64 v13, v89, v251, s[62:63]
	v_cndmask_b32_e64 v18, v248, v90, s[62:63]
	v_cndmask_b32_e64 v19, v249, v91, s[62:63]
	v_mov_b32_dpp v248, v92 quad_perm:[1,0,3,2] row_mask:0xf bank_mask:0xf
	v_mov_b32_dpp v249, v93 quad_perm:[1,0,3,2] row_mask:0xf bank_mask:0xf
	v_mov_b32_dpp v250, v94 quad_perm:[1,0,3,2] row_mask:0xf bank_mask:0xf
	v_mov_b32_dpp v251, v95 quad_perm:[1,0,3,2] row_mask:0xf bank_mask:0xf
	v_cndmask_b32_e64 v22, v92, v250, s[62:63]
	v_cndmask_b32_e64 v23, v93, v251, s[62:63]
	v_cndmask_b32_e64 v20, v248, v94, s[62:63]
	v_cndmask_b32_e64 v21, v249, v95, s[62:63]
	v_mov_b32_dpp v248, v96 quad_perm:[1,0,3,2] row_mask:0xf bank_mask:0xf
	v_mov_b32_dpp v249, v97 quad_perm:[1,0,3,2] row_mask:0xf bank_mask:0xf
	v_mov_b32_dpp v250, v98 quad_perm:[1,0,3,2] row_mask:0xf bank_mask:0xf
	v_mov_b32_dpp v251, v99 quad_perm:[1,0,3,2] row_mask:0xf bank_mask:0xf
	v_cndmask_b32_e64 v28, v96, v250, s[62:63]
	v_cndmask_b32_e64 v29, v97, v251, s[62:63]
	v_cndmask_b32_e64 v30, v248, v98, s[62:63]
	v_cndmask_b32_e64 v31, v249, v99, s[62:63]
	v_mov_b32_dpp v248, v100 quad_perm:[1,0,3,2] row_mask:0xf bank_mask:0xf
	v_mov_b32_dpp v249, v101 quad_perm:[1,0,3,2] row_mask:0xf bank_mask:0xf
	v_mov_b32_dpp v250, v102 quad_perm:[1,0,3,2] row_mask:0xf bank_mask:0xf
	v_mov_b32_dpp v251, v103 quad_perm:[1,0,3,2] row_mask:0xf bank_mask:0xf
	v_cndmask_b32_e64 v24, v100, v250, s[62:63]
	v_cndmask_b32_e64 v25, v101, v251, s[62:63]
	v_cndmask_b32_e64 v26, v248, v102, s[62:63]
	v_cndmask_b32_e64 v27, v249, v103, s[62:63]
	v_mov_b32_e32 v104, v110
	v_mov_b32_e32 v105, v111
	v_lshl_add_u64 v[104:105], v[104:105], 0, v[246:247]
	s_mov_b32 s51, 0
	s_cmp_lg_u32 s50, 0
	s_cbranch_scc1 .Lp7n_nopref
	v_lshl_add_u64 v[110:111], s[26:27], 0, v[4:5]
	v_add_co_u32_e32 v118, vcc, s23, v110
	s_ashr_i32 s0, s37, 9
	s_nop 0
	v_addc_co_u32_e32 v119, vcc, 0, v111, vcc
	v_add_co_u32_e32 v120, vcc, s33, v110
	v_lshl_add_u64 v[112:113], s[12:13], 0, v[4:5]
	s_nop 0
	v_addc_co_u32_e32 v121, vcc, 0, v111, vcc
	s_and_b32 s1, s17, 0xffe0
	s_lshl_b32 s0, s0, 3
	v_add_co_u32_e32 v110, vcc, s35, v112
	s_lshl_b32 s28, s1, 1
	s_nop 0
	v_addc_co_u32_e32 v111, vcc, 0, v113, vcc
	v_lshl_add_u64 v[118:119], v[118:119], 0, v[252:253]
	v_lshl_add_u64 v[120:121], v[120:121], 0, v[252:253]
	global_load_dwordx4 v[88:91], v[118:119], off offset:3744 nt
	s_nop 0
	s_nop 0
	global_load_dwordx4 v[92:95], v[120:121], off offset:672 nt
	s_nop 0
	s_nop 0
	s_and_b32 s1, s0, 0xffffffe0
	v_or_b32_e32 v126, s0, v17
	v_or_b32_e32 v128, s1, v14
	v_or_b32_e32 v130, s1, v15
	v_or_b32_e32 v132, s1, v16
	v_ashrrev_i32_e32 v127, 31, v126
	v_ashrrev_i32_e32 v129, 31, v128
	v_ashrrev_i32_e32 v131, 31, v130
	v_ashrrev_i32_e32 v133, 31, v132
	v_lshl_add_u64 v[124:125], v[6:7], 0, s[28:29]
	v_lshlrev_b64 v[126:127], 17, v[126:127]
	v_lshlrev_b64 v[128:129], 17, v[128:129]
	v_lshlrev_b64 v[130:131], 17, v[130:131]
	v_lshlrev_b64 v[132:133], 17, v[132:133]
	v_lshl_add_u64 v[126:127], v[124:125], 0, v[126:127]
	v_lshl_add_u64 v[128:129], v[124:125], 0, v[128:129]
	v_lshl_add_u64 v[130:131], v[124:125], 0, v[130:131]
	v_lshl_add_u64 v[124:125], v[124:125], 0, v[132:133]
	v_lshl_add_u64 v[128:129], v[128:129], 0, v[254:255]
	v_lshl_add_u64 v[124:125], v[124:125], 0, v[254:255]
	global_load_dwordx4 v[96:99], v[128:129], off nt
	s_nop 0
	s_nop 0
	s_nop 0
	global_load_dwordx4 v[100:103], v[124:125], off nt
	s_nop 0
	s_nop 0
	s_add_i32 s37, s37, s96
	s_add_u32 s12, s12, s24
	s_addc_u32 s13, s13, s25
	s_add_u32 s26, s26, s16
	s_addc_u32 s27, s27, s14
	s_add_i32 s17, s17, s22
	s_cmpk_gt_i32 s37, 0x3fff
	s_cselect_b32 s50, 1, 0
	s_mov_b32 s51, 1
